# attention: V tile staged as a quad-interleaved image with 144-byte rows so each V fragment is one 16-byte LDS read; last key tile handled inside the loop
# speedup vs baseline: 1.0139x; 1.0139x over previous
.LBB0_130:
	s_or_b64 exec, exec, s[20:21]
	v_add_u32_e32 v4, 0, v4
	v_cmp_lt_i32_e32 vcc, v231, v230
	s_waitcnt vmcnt(0)
	ds_write2_b64 v4, v[0:1], v[2:3] offset1:1
	v_mov_b32_e32 v138, 0
	v_cndmask_b32_e32 v0, v229, v231, vcc
	s_ashr_i32 s5, s4, 31
	s_mov_b32 s35, 0
	v_lshlrev_b32_e32 v135, 2, v0
	v_mov_b32_e32 v147, 0xff800000
	v_mov_b32_e32 v80, v120
	v_mov_b32_e32 v104, v146
	v_mov_b32_e32 v136, v145
	v_mov_b32_e32 v16, 0
	v_mov_b32_e32 v17, v138
	v_mov_b32_e32 v18, v138
	v_mov_b32_e32 v19, v138
	v_mov_b32_e32 v20, v138
	v_mov_b32_e32 v21, v138
	v_mov_b32_e32 v22, v138
	v_mov_b32_e32 v23, v138
	v_mov_b32_e32 v24, v138
	v_mov_b32_e32 v25, v138
	v_mov_b32_e32 v26, v138
	v_mov_b32_e32 v27, v138
	v_mov_b32_e32 v28, v138
	v_mov_b32_e32 v29, v138
	v_mov_b32_e32 v30, v138
	v_mov_b32_e32 v31, v138
	v_mov_b32_e32 v0, 0
	v_mov_b32_e32 v1, v138
	v_mov_b32_e32 v2, v138
	v_mov_b32_e32 v3, v138
	v_mov_b32_e32 v4, v138
	v_mov_b32_e32 v5, v138
	v_mov_b32_e32 v6, v138
	v_mov_b32_e32 v7, v138
	v_mov_b32_e32 v8, v138
	v_mov_b32_e32 v9, v138
	v_mov_b32_e32 v10, v138
	v_mov_b32_e32 v11, v138
	v_mov_b32_e32 v12, v138
	v_mov_b32_e32 v13, v138
	v_mov_b32_e32 v14, v138
	v_mov_b32_e32 v15, v138
	s_waitcnt lgkmcnt(0)
	s_barrier
	v_readfirstlane_b32 s85, v204
	s_mov_b32 s76, 1
	s_movk_i32 s77, 0x3400
	s_mov_b32 s78, 0xf400
	s_mov_b32 s79, 0x11800
	s_mov_b32 s80, 0xd000
	s_movk_i32 s81, 0x3400
	s_mov_b32 s82, 0xd000
	s_mov_b32 s83, 0xf400
	s_mov_b32 s84, 0x11800
	s_lshr_b32 s85, s85, 8
	s_mov_b32 s35, 0
	s_mov_b32 s87, 0x44800000
	v_mov_b32_e32 v105, v81
	v_mov_b32_e32 v137, v81
	v_lshrrev_b32_e32 v239, 3, v204
	v_xor_b32_e32 v239, 32, v239
	v_mul_u32_u24_e32 v239, 0x90, v239
	v_and_b32_e32 v242, 6, v204
	v_lshl_add_u32 v239, v242, 4, v239
	v_and_b32_e32 v242, 1, v204
	v_lshl_add_u32 v239, v242, 3, v239
	v_and_b32_e32 v205, 31, v229
	v_mul_u32_u24_e32 v205, 0x90, v205
	v_lshrrev_b32_e32 v242, 5, v229
	v_lshl_add_u32 v205, v242, 4, v205
	s_cmp_eq_u32 s85, 0
	s_cbranch_scc0 .Lat_v0B
	v_lshl_add_u64 v[240:241], v[116:117], 1, s[8:9]
	s_branch .Lat_v0L
.Lat_v0B:
	v_lshl_add_u64 v[240:241], v[132:133], 1, v[102:103]
.Lat_v0L:
	global_load_dwordx4 v[244:247], v[240:241], off
	v_lshl_add_u64 v[240:241], v[80:81], 1, s[6:7]
	global_load_dwordx4 v[98:101], v[240:241], off
	v_lshl_add_u64 v[240:241], v[104:105], 1, v[102:103]
	global_load_dwordx4 v[94:97], v[240:241], off
	s_cmp_eq_u32 s85, 0
	s_cbranch_scc0 .Lat_ld1
	v_lshl_add_u64 v[240:241], v[136:137], 1, s[8:9]
	global_load_dwordx4 v[90:93], v[240:241], off
.Lat_ld1:
	v_add_u32_e32 v80, 0x1800, v80
	v_add_u32_e32 v104, v104, v144
	v_add_u32_e32 v136, 64, v136
	ds_read_b128 v[206:209], v142
	ds_read_b128 v[210:213], v142 offset:32
	ds_read_b128 v[214:217], v142 offset:64
	ds_read_b128 v[218:221], v142 offset:96
	ds_read_b128 v[222:225], v142 offset:128
	ds_read_b128 v[164:167], v142 offset:160
	ds_read_b128 v[148:151], v142 offset:6656
	ds_read_b128 v[152:155], v142 offset:6688
	ds_read_b128 v[184:187], v142 offset:6720
	ds_read_b128 v[188:191], v142 offset:6752
	ds_read_b128 v[192:195], v142 offset:6784
	ds_read_b128 v[200:203], v142 offset:6816
	s_waitcnt lgkmcnt(11)
	v_mfma_f32_32x32x16_bf16 v[48:63], v[206:209], v[86:89], 0
	s_waitcnt lgkmcnt(10)
	v_mfma_f32_32x32x16_bf16 v[48:63], v[210:213], v[82:85], v[48:63]
	s_waitcnt lgkmcnt(9)
	v_mfma_f32_32x32x16_bf16 v[48:63], v[214:217], v[76:79], v[48:63]
	s_waitcnt lgkmcnt(8)
	v_mfma_f32_32x32x16_bf16 v[48:63], v[218:221], v[72:75], v[48:63]
	s_waitcnt lgkmcnt(7)
	v_mfma_f32_32x32x16_bf16 v[48:63], v[222:225], v[68:71], v[48:63]
	s_waitcnt lgkmcnt(6)
	v_mfma_f32_32x32x16_bf16 v[48:63], v[164:167], v[64:67], v[48:63]
	s_waitcnt lgkmcnt(5)
	v_mfma_f32_32x32x16_bf16 v[32:47], v[148:151], v[86:89], 0
	s_waitcnt lgkmcnt(4)
	v_mfma_f32_32x32x16_bf16 v[32:47], v[152:155], v[82:85], v[32:47]
	s_waitcnt lgkmcnt(3)
	v_mfma_f32_32x32x16_bf16 v[32:47], v[184:187], v[76:79], v[32:47]
	s_waitcnt lgkmcnt(2)
	v_mfma_f32_32x32x16_bf16 v[32:47], v[188:191], v[72:75], v[32:47]
	s_waitcnt lgkmcnt(1)
	v_mfma_f32_32x32x16_bf16 v[32:47], v[192:195], v[68:71], v[32:47]
	s_waitcnt lgkmcnt(0)
	v_mfma_f32_32x32x16_bf16 v[32:47], v[200:203], v[64:67], v[32:47]
	s_cmpk_gt_u32 s76, 0x47
	s_cbranch_scc1 .Lat_nost2
	s_waitcnt vmcnt(0)
	v_add_u32_e32 v242, s77, v109
	ds_write_b128 v242, v[98:101]
	s_cmp_eq_u32 s85, 0
	s_cbranch_scc0 .Lat_stB3
	v_add_u32_e32 v242, s77, v140
	ds_write_b128 v242, v[94:97]
	v_add_u32_e32 v242, s78, v239
	ds_write2_b64 v242, v[90:91], v[92:93] offset1:2
	s_branch .Lat_std4
.Lat_stB3:
	v_add_u32_e32 v242, s78, v239
	ds_write2_b64 v242, v[94:95], v[96:97] offset1:2

.Lat_nost2:
	v_add_u32_e32 v242, s82, v239
	ds_write2_b64 v242, v[244:245], v[246:247] offset1:2
	s_nop 7
	s_nop 3
	v_max3_f32 v128, v48, v49, v50
	v_max3_f32 v128, v128, v51, v52
	v_max3_f32 v128, v128, v53, v54
	v_max3_f32 v128, v128, v55, v56
	v_max3_f32 v128, v128, v57, v58
	v_max3_f32 v128, v128, v59, v60
	v_max3_f32 v128, v128, v61, v62
	v_max3_f32 v128, v128, v63, v32
	v_max3_f32 v128, v128, v33, v34
	v_max3_f32 v128, v128, v35, v36
	v_max3_f32 v128, v128, v37, v38
	v_max3_f32 v128, v128, v39, v40
	v_max3_f32 v128, v128, v41, v42
	v_max3_f32 v128, v128, v43, v44
	v_max3_f32 v128, v128, v45, v46
	v_max_f32_e32 v128, v128, v47
	v_mov_b32_e32 v129, v128
	s_nop 1
	v_permlane32_swap_b32_e32 v128, v129
	v_max_f32_e32 v128, v128, v129
	v_sub_f32_e32 v168, 0, v128
	v_sub_f32_e32 v169, 0, v128
	v_sub_f32_e32 v170, 0, v128
	v_sub_f32_e32 v171, 0, v128
	v_sub_f32_e32 v172, 0, v128
	v_sub_f32_e32 v173, 0, v128
	v_sub_f32_e32 v174, 0, v128
	v_sub_f32_e32 v175, 0, v128
	v_sub_f32_e32 v176, 0, v128
	v_sub_f32_e32 v177, 0, v128
	v_sub_f32_e32 v178, 0, v128
	v_sub_f32_e32 v179, 0, v128
	v_sub_f32_e32 v180, 0, v128
	v_sub_f32_e32 v181, 0, v128
	v_sub_f32_e32 v182, 0, v128
	v_sub_f32_e32 v183, 0, v128
	v_sub_f32_e32 v48, v48, v128
	v_sub_f32_e32 v49, v49, v128
	v_sub_f32_e32 v50, v50, v128
	v_sub_f32_e32 v51, v51, v128
	v_sub_f32_e32 v52, v52, v128
	v_sub_f32_e32 v53, v53, v128
	v_sub_f32_e32 v54, v54, v128
	v_sub_f32_e32 v55, v55, v128
	v_sub_f32_e32 v56, v56, v128
	v_sub_f32_e32 v57, v57, v128
	v_sub_f32_e32 v58, v58, v128
	v_sub_f32_e32 v59, v59, v128
	v_sub_f32_e32 v60, v60, v128
	v_sub_f32_e32 v61, v61, v128
	v_sub_f32_e32 v62, v62, v128
	v_sub_f32_e32 v63, v63, v128
	v_sub_f32_e32 v32, v32, v128
	v_sub_f32_e32 v33, v33, v128
	v_sub_f32_e32 v34, v34, v128
	v_sub_f32_e32 v35, v35, v128
	v_sub_f32_e32 v36, v36, v128
	v_sub_f32_e32 v37, v37, v128
	v_sub_f32_e32 v38, v38, v128
	v_sub_f32_e32 v39, v39, v128
	v_sub_f32_e32 v40, v40, v128
	v_sub_f32_e32 v41, v41, v128
	v_sub_f32_e32 v42, v42, v128
	v_sub_f32_e32 v43, v43, v128
	v_sub_f32_e32 v44, v44, v128
	v_sub_f32_e32 v45, v45, v128
	v_sub_f32_e32 v46, v46, v128
	v_sub_f32_e32 v47, v47, v128
	v_exp_f32_e32 v48, v48
	v_exp_f32_e32 v49, v49
	v_exp_f32_e32 v50, v50
	v_exp_f32_e32 v51, v51
	v_exp_f32_e32 v52, v52
	v_exp_f32_e32 v53, v53
	v_exp_f32_e32 v54, v54
	v_exp_f32_e32 v55, v55
	v_exp_f32_e32 v56, v56
	v_exp_f32_e32 v57, v57
	v_exp_f32_e32 v58, v58
	v_exp_f32_e32 v59, v59
	v_exp_f32_e32 v60, v60
	v_exp_f32_e32 v61, v61
	v_exp_f32_e32 v62, v62
	v_exp_f32_e32 v63, v63
	v_cvt_pk_bf16_f32 v148, v48, v49
	v_cvt_pk_bf16_f32 v149, v50, v51
	v_cvt_pk_bf16_f32 v150, v52, v53
	v_cvt_pk_bf16_f32 v151, v54, v55
	v_cvt_pk_bf16_f32 v152, v56, v57
	v_cvt_pk_bf16_f32 v153, v58, v59
	v_cvt_pk_bf16_f32 v154, v60, v61
	v_cvt_pk_bf16_f32 v155, v62, v63
	s_waitcnt lgkmcnt(0)
	s_barrier
	v_add_u32_e32 v129, s82, v205
	ds_read_b128 v[184:187], v129
	ds_read_b128 v[188:191], v129 offset:4608
	ds_read_b128 v[192:195], v129 offset:32
	ds_read_b128 v[200:203], v129 offset:4640
	s_mov_b32 s86, s82
	s_mov_b32 s82, s83
	s_mov_b32 s83, s84
	s_mov_b32 s84, s86
.Lat_loop:
	v_add_u32_e32 v130, s81, v142
	ds_read_b128 v[206:209], v130
	ds_read_b128 v[210:213], v130 offset:32
	s_waitcnt lgkmcnt(5)
	v_mfma_f32_32x32x16_bf16 v[16:31], v[184:187], v[148:151], v[16:31]
	ds_read_b128 v[184:187], v129 offset:64
	v_add_f32_e32 v226, v48, v49
	v_add_f32_e32 v227, v56, v57
	v_add_f32_e32 v226, v226, v50
	ds_read_b128 v[214:217], v130 offset:64
	ds_read_b128 v[218:221], v130 offset:96
	s_waitcnt lgkmcnt(7)
	v_mfma_f32_32x32x16_bf16 v[0:15], v[188:191], v[148:151], v[0:15]
	ds_read_b128 v[188:191], v129 offset:4672
	v_add_f32_e32 v227, v227, v58
	v_add_f32_e32 v226, v226, v51
	v_add_f32_e32 v227, v227, v59
	v_add_f32_e32 v226, v226, v52
	ds_read_b128 v[222:225], v130 offset:128
	ds_read_b128 v[164:167], v130 offset:160
	s_waitcnt lgkmcnt(9)
	v_mfma_f32_32x32x16_bf16 v[16:31], v[192:195], v[152:155], v[16:31]
	ds_read_b128 v[192:195], v129 offset:96
	v_add_f32_e32 v227, v227, v60
	v_add_f32_e32 v226, v226, v53
	v_add_f32_e32 v227, v227, v61
	s_waitcnt lgkmcnt(9)
	v_mfma_f32_32x32x16_bf16 v[0:15], v[200:203], v[152:155], v[0:15]
	ds_read_b128 v[200:203], v129 offset:4704
	v_add_f32_e32 v226, v226, v54
	v_add_f32_e32 v227, v227, v62
	v_add_f32_e32 v226, v226, v55
	v_add_f32_e32 v227, v227, v63
	s_waitcnt lgkmcnt(2)
	v_mfma_f32_32x32x16_bf16 v[48:63], v[206:209], v[86:89], v[168:183]
	ds_read_b128 v[206:209], v130 offset:6656
	v_exp_f32_e32 v32, v32
	v_exp_f32_e32 v33, v33
	v_mfma_f32_32x32x16_bf16 v[48:63], v[210:213], v[82:85], v[48:63]
	ds_read_b128 v[210:213], v130 offset:6688
	v_exp_f32_e32 v34, v34
	v_exp_f32_e32 v35, v35
	v_exp_f32_e32 v36, v36
	v_mfma_f32_32x32x16_bf16 v[48:63], v[214:217], v[76:79], v[48:63]
	ds_read_b128 v[214:217], v130 offset:6720
	v_exp_f32_e32 v37, v37
	v_exp_f32_e32 v38, v38
	v_exp_f32_e32 v39, v39
	v_mfma_f32_32x32x16_bf16 v[48:63], v[218:221], v[72:75], v[48:63]
	ds_read_b128 v[218:221], v130 offset:6752
	v_exp_f32_e32 v40, v40
	v_exp_f32_e32 v41, v41
	v_mfma_f32_32x32x16_bf16 v[48:63], v[222:225], v[68:71], v[48:63]
	ds_read_b128 v[222:225], v130 offset:6784
	v_exp_f32_e32 v42, v42
	v_exp_f32_e32 v43, v43
	v_exp_f32_e32 v44, v44
	v_mfma_f32_32x32x16_bf16 v[48:63], v[164:167], v[64:67], v[48:63]
	ds_read_b128 v[164:167], v130 offset:6816
	v_exp_f32_e32 v45, v45
	v_exp_f32_e32 v46, v46
	v_exp_f32_e32 v47, v47
	v_cvt_pk_bf16_f32 v156, v32, v33
	v_cvt_pk_bf16_f32 v157, v34, v35
	v_cvt_pk_bf16_f32 v158, v36, v37
	v_cvt_pk_bf16_f32 v159, v38, v39
	v_cvt_pk_bf16_f32 v160, v40, v41
	v_cvt_pk_bf16_f32 v161, v42, v43
	v_cvt_pk_bf16_f32 v162, v44, v45
	v_cvt_pk_bf16_f32 v163, v46, v47
	v_mfma_f32_32x32x16_bf16 v[16:31], v[184:187], v[156:159], v[16:31]
	v_add_f32_e32 v248, v32, v33
	v_add_f32_e32 v249, v40, v41
	v_add_f32_e32 v248, v248, v34
	v_add_f32_e32 v249, v249, v42
	v_add_f32_e32 v248, v248, v35
	v_mfma_f32_32x32x16_bf16 v[0:15], v[188:191], v[156:159], v[0:15]
	v_add_f32_e32 v249, v249, v43
	v_add_f32_e32 v248, v248, v36
	v_add_f32_e32 v249, v249, v44
	v_add_f32_e32 v248, v248, v37
	v_add_f32_e32 v249, v249, v45
	s_waitcnt lgkmcnt(7)
	v_mfma_f32_32x32x16_bf16 v[16:31], v[192:195], v[160:163], v[16:31]
	v_add_f32_e32 v248, v248, v38
	v_add_f32_e32 v249, v249, v46
	v_add_f32_e32 v248, v248, v39
	v_add_f32_e32 v249, v249, v47
	v_add_f32_e32 v226, v226, v227
	s_waitcnt lgkmcnt(6)
	v_mfma_f32_32x32x16_bf16 v[0:15], v[200:203], v[160:163], v[0:15]
	v_add_f32_e32 v248, v248, v249
	v_add_f32_e32 v226, v226, v248
	v_cmp_lt_f32_e32 vcc, s87, v226
	s_mov_b64 s[88:89], vcc
	v_add_f32_e32 v138, v138, v226
	s_waitcnt lgkmcnt(0)
	v_mfma_f32_32x32x16_bf16 v[32:47], v[206:209], v[86:89], v[168:183]
	v_exp_f32_e32 v48, v48
	v_exp_f32_e32 v49, v49
	v_exp_f32_e32 v50, v50
	v_mfma_f32_32x32x16_bf16 v[32:47], v[210:213], v[82:85], v[32:47]
	v_exp_f32_e32 v51, v51
	v_exp_f32_e32 v52, v52
	v_exp_f32_e32 v53, v53
	v_mfma_f32_32x32x16_bf16 v[32:47], v[214:217], v[76:79], v[32:47]
	v_exp_f32_e32 v54, v54
	v_exp_f32_e32 v55, v55
	v_exp_f32_e32 v56, v56
	v_mfma_f32_32x32x16_bf16 v[32:47], v[218:221], v[72:75], v[32:47]
	v_exp_f32_e32 v57, v57
	v_exp_f32_e32 v58, v58
	v_exp_f32_e32 v59, v59
	v_mfma_f32_32x32x16_bf16 v[32:47], v[222:225], v[68:71], v[32:47]
	v_exp_f32_e32 v60, v60
	v_exp_f32_e32 v61, v61
	v_exp_f32_e32 v62, v62
	v_mfma_f32_32x32x16_bf16 v[32:47], v[164:167], v[64:67], v[32:47]
	v_exp_f32_e32 v63, v63
	v_cvt_pk_bf16_f32 v148, v48, v49
	v_cvt_pk_bf16_f32 v149, v50, v51
	v_cvt_pk_bf16_f32 v150, v52, v53
	v_cvt_pk_bf16_f32 v151, v54, v55
	v_cvt_pk_bf16_f32 v152, v56, v57
	v_cvt_pk_bf16_f32 v153, v58, v59
	v_cvt_pk_bf16_f32 v154, v60, v61
	v_cvt_pk_bf16_f32 v155, v62, v63
	s_cmpk_gt_u32 s76, 0x47
	s_cbranch_scc1 .Lat_nost6
	s_waitcnt vmcnt(0)
	v_add_u32_e32 v242, s77, v109
	ds_write_b128 v242, v[98:101]
	s_cmp_eq_u32 s85, 0
	s_cbranch_scc0 .Lat_stB7
	v_add_u32_e32 v242, s77, v140
	ds_write_b128 v242, v[94:97]
	v_add_u32_e32 v242, s78, v239
	ds_write2_b64 v242, v[90:91], v[92:93] offset1:2
	s_branch .Lat_std8

.Lat_nost6:
	v_add_u32_e32 v129, s82, v205
	ds_read_b128 v[184:187], v129
	ds_read_b128 v[188:191], v129 offset:4608
	ds_read_b128 v[192:195], v129 offset:32
	ds_read_b128 v[200:203], v129 offset:4640
	s_mov_b32 s86, s82
	s_mov_b32 s82, s83
	s_mov_b32 s83, s84
	s_mov_b32 s84, s86
	s_xor_b32 s81, s81, 0x3400
	s_add_i32 s35, s35, 1
	s_cmp_lg_u64 s[88:89], 0
	s_cbranch_scc1 .Lat_resc
.Lat_resc_back:
	s_cmpk_lt_u32 s35, 0x48
	s_waitcnt lgkmcnt(4)
	s_barrier
	s_cbranch_scc1 .Lat_loop
	s_waitcnt lgkmcnt(0)
	s_nop 7
	s_nop 7
	s_lshl_b64 s[4:5], s[4:5], 11
	s_add_u32 s4, s2, s4
	s_addc_u32 s5, s3, s5
	s_lshl_b32 s6, s10, 7
	s_add_u32 s4, s4, s6
	s_addc_u32 s5, s5, 0
	v_mov_b32_e32 v33, v138
	ds_bpermute_b32 v32, v135, v33
	s_branch .LBB0_106
